# gemm_phase prologues (8 sites): both LDS-DMA batches (tile 0 and tile 1) issued together; the younger half's stagger barrier and the first counted wait (vmcnt(8)) follow both (on top of v25)
# baseline (speedup 1.0000x reference)
.LBB0_125:
	s_and_b32 s7, s8, 3
	s_mov_b64 s[8:9], 0x80
	s_add_i32 m0, s29, 0x18000
	v_lshl_add_u64 v[12:13], v[12:13], 0, s[8:9]
	global_load_lds_dwordx4 v[12:13], off
	v_lshl_add_u64 v[10:11], v[10:11], 0, s[8:9]
	s_add_i32 m0, s29, 0x1a000
	s_add_i32 s52, s29, 0x8000
	s_lshl_b32 s50, s10, 6
	s_lshl_b32 s11, s10, 13
	s_lshl_b32 s51, s7, 5
	s_lshl_b32 s14, s7, 12
	global_load_lds_dwordx4 v[10:11], off
	v_lshl_add_u64 v[6:7], v[6:7], 0, s[8:9]
	s_mov_b32 m0, s52
	s_add_i32 s53, s29, 0xa000
	global_load_lds_dwordx4 v[6:7], off
	v_lshl_add_u64 v[6:7], v[8:9], 0, s[8:9]
	s_add_u32 s8, s30, 0x100080
	s_mov_b32 m0, s53
	s_addc_u32 s9, s31, 0
	global_load_lds_dwordx4 v[6:7], off
	s_add_i32 m0, s29, 0x1c000
	v_lshl_add_u64 v[6:7], s[8:9], 0, v[134:135]
	global_load_lds_dwordx4 v[6:7], off
	v_lshl_add_u64 v[6:7], s[8:9], 0, v[138:139]
	s_add_i32 m0, s29, 0x1e000
	v_and_b32_e32 v5, 48, v1
	global_load_lds_dwordx4 v[6:7], off
	v_readlane_b32 s100, v253, 51
	s_nop 3
	s_cmp_lt_u32 s100, 4
	s_cbranch_scc1 .Lpro_nostag_1
	s_barrier
.Lpro_nostag_1:
	s_waitcnt vmcnt(8)
	s_barrier
	v_lshlrev_b32_e32 v6, 6, v1
	s_movk_i32 s8, 0x3c0
	v_lshlrev_b32_e32 v1, 2, v1
	v_and_or_b32 v5, v6, s8, v5
	v_and_b32_e32 v1, 32, v1
	s_cmpk_lt_u32 s2, 0x100
	v_bitop3_b32 v6, v5, s11, v1 bitop3:0xde
	s_cselect_b64 s[8:9], -1, 0
	s_lshl_b32 s2, s10, 11
	v_readlane_b32 s10, v254, 28
	s_lshl_b32 s7, s7, 2
	v_readlane_b32 s11, v254, 29
	s_add_i32 s7, s7, 0
	s_mov_b32 s15, s11
	s_waitcnt vmcnt(6)
	s_add_i32 s54, s7, s2
	s_mov_b32 s7, s15
	v_bitop3_b32 v1, v5, s14, v1 bitop3:0xde
	s_mov_b32 s19, s11
	s_lshl_b32 s14, s70, 7
	v_writelane_b32 v254, s6, 28
	s_add_i32 s54, s54, 0x20000
	s_mov_b32 s2, 0
	v_add_u32_e32 v5, 0, v6
	s_lshl_b64 s[10:11], s[18:19], 2
	v_writelane_b32 v254, s7, 29
	s_lshl_b64 s[14:15], s[14:15], 2
	s_barrier
	s_branch .LBB0_128

.LBB0_246:
	v_mov_b32_e32 v137, v4
	s_lshl_b32 s43, s6, 6
	v_and_b32_e32 v5, 48, v1
	s_lshl_b32 s1, s6, 13
	v_lshlrev_b32_e32 v14, 6, v1
	s_movk_i32 s6, 0x3c0
	v_lshlrev_b32_e32 v1, 2, v1
	v_lshl_add_u64 v[6:7], s[24:25], 0, v[136:137]
	v_mov_b32_e32 v3, v4
	v_and_or_b32 v5, v14, s6, v5
	v_and_b32_e32 v1, 32, v1
	s_mov_b64 s[6:7], 0x80
	v_lshl_add_u64 v[8:9], s[24:25], 0, v[2:3]
	v_mov_b32_e32 v139, v4
	v_bitop3_b32 v14, v5, s1, v1 bitop3:0xde
	s_lshl_b32 s1, s2, 5
	s_add_i32 m0, s23, 0x18000
	v_lshl_add_u64 v[6:7], v[6:7], 0, s[6:7]
	v_lshl_add_u64 v[10:11], s[26:27], 0, v[138:139]
	v_mov_b32_e32 v135, v4
	s_and_b32 s48, s1, 0x60
	global_load_lds_dwordx4 v[6:7], off
	v_lshl_add_u64 v[6:7], v[8:9], 0, s[6:7]
	s_add_i32 m0, s23, 0x1a000
	s_add_i32 s49, s23, 0x8000
	v_lshl_add_u64 v[12:13], s[26:27], 0, v[134:135]
	s_lshl_b32 s1, s48, 7
	global_load_lds_dwordx4 v[6:7], off
	v_lshl_add_u64 v[6:7], v[10:11], 0, s[6:7]
	s_mov_b32 m0, s49
	s_add_i32 s50, s23, 0xa000
	global_load_lds_dwordx4 v[6:7], off
	v_lshl_add_u64 v[6:7], v[12:13], 0, s[6:7]
	s_add_u32 s6, s24, 0x100080
	s_mov_b32 m0, s50
	s_addc_u32 s7, s25, 0
	global_load_lds_dwordx4 v[6:7], off
	s_add_i32 m0, s23, 0x1c000
	v_lshl_add_u64 v[6:7], s[6:7], 0, v[136:137]
	global_load_lds_dwordx4 v[6:7], off
	v_lshl_add_u64 v[6:7], s[6:7], 0, v[2:3]
	s_add_i32 m0, s23, 0x1e000
	v_readlane_b32 s6, v254, 28
	global_load_lds_dwordx4 v[6:7], off
	v_readlane_b32 s100, v253, 51
	s_nop 3
	s_cmp_lt_u32 s100, 4
	s_cbranch_scc1 .Lpro_nostag_2
	s_barrier
.Lpro_nostag_2:
	s_waitcnt vmcnt(8)
	s_barrier
	s_waitcnt vmcnt(6)
	v_readlane_b32 s7, v254, 29
	s_mov_b32 s19, s7
	v_bitop3_b32 v1, s1, v5, v1 bitop3:0xf6
	s_mov_b32 s51, 0
	v_add_u32_e32 v5, 0, v14
	s_lshl_b64 s[6:7], s[18:19], 2
	s_barrier
	s_branch .LBB0_248

.LBB0_337:
	s_lshl_b32 s47, s2, 6
	v_and_b32_e32 v5, 48, v1
	s_lshl_b32 s1, s2, 13
	v_lshlrev_b32_e32 v14, 6, v1
	s_movk_i32 s2, 0x3c0
	v_lshlrev_b32_e32 v1, 2, v1
	v_mov_b32_e32 v135, v4
	v_and_or_b32 v5, v14, s2, v5
	v_and_b32_e32 v1, 32, v1
	v_lshl_add_u64 v[6:7], s[24:25], 0, v[134:135]
	v_mov_b32_e32 v139, v4
	v_bitop3_b32 v14, v5, s1, v1 bitop3:0xde
	s_lshl_b32 s1, s6, 5
	s_mov_b64 s[6:7], 0x80
	v_lshl_add_u64 v[8:9], s[24:25], 0, v[138:139]
	v_mov_b32_e32 v3, v4
	s_add_i32 m0, s41, 0x18000
	v_lshl_add_u64 v[6:7], v[6:7], 0, s[6:7]
	v_lshl_add_u64 v[10:11], s[26:27], 0, v[2:3]
	v_mov_b32_e32 v137, v4
	s_and_b32 s48, s1, 0x60
	global_load_lds_dwordx4 v[6:7], off
	v_lshl_add_u64 v[6:7], v[8:9], 0, s[6:7]
	s_add_i32 m0, s41, 0x1a000
	s_add_i32 s49, s41, 0x8000
	v_lshl_add_u64 v[12:13], s[26:27], 0, v[136:137]
	s_lshl_b32 s1, s48, 7
	global_load_lds_dwordx4 v[6:7], off
	v_lshl_add_u64 v[6:7], v[10:11], 0, s[6:7]
	s_mov_b32 m0, s49
	s_add_i32 s50, s41, 0xa000
	global_load_lds_dwordx4 v[6:7], off
	v_lshl_add_u64 v[6:7], v[12:13], 0, s[6:7]
	s_add_u32 s6, s24, 0x100080
	s_mov_b32 m0, s50
	s_addc_u32 s7, s25, 0
	global_load_lds_dwordx4 v[6:7], off
	s_add_i32 m0, s41, 0x1c000
	v_lshl_add_u64 v[6:7], s[6:7], 0, v[134:135]
	global_load_lds_dwordx4 v[6:7], off
	v_lshl_add_u64 v[6:7], s[6:7], 0, v[138:139]
	s_add_i32 m0, s41, 0x1e000
	v_readlane_b32 s6, v254, 28
	global_load_lds_dwordx4 v[6:7], off
	v_readlane_b32 s100, v253, 51
	s_nop 3
	s_cmp_lt_u32 s100, 4
	s_cbranch_scc1 .Lpro_nostag_3
	s_barrier

.LBB0_444:
	v_and_b32_e32 v5, 48, v1
	v_lshlrev_b32_e32 v14, 6, v1
	s_movk_i32 s8, 0x3c0
	v_and_or_b32 v5, v14, s8, v5
	s_mov_b64 s[8:9], 0x80
	v_lshlrev_b32_e32 v1, 2, v1
	s_add_i32 m0, s29, 0x18000
	v_lshl_add_u64 v[12:13], v[12:13], 0, s[8:9]
	s_and_b32 s10, s3, 3
	s_lshl_b32 s7, s6, 13
	v_and_b32_e32 v1, 32, v1
	global_load_lds_dwordx4 v[12:13], off
	v_lshl_add_u64 v[10:11], v[10:11], 0, s[8:9]
	s_add_i32 m0, s29, 0x1a000
	s_add_i32 s56, s29, 0x8000
	s_lshl_b32 s54, s6, 6
	v_bitop3_b32 v14, v5, s7, v1 bitop3:0xde
	s_lshl_b32 s55, s10, 5
	s_lshl_b32 s7, s10, 12
	global_load_lds_dwordx4 v[10:11], off
	v_lshl_add_u64 v[6:7], v[6:7], 0, s[8:9]
	s_mov_b32 m0, s56
	s_add_i32 s57, s29, 0xa000
	global_load_lds_dwordx4 v[6:7], off
	v_lshl_add_u64 v[6:7], v[8:9], 0, s[8:9]
	s_add_u32 s8, s34, 0x40080
	s_mov_b32 m0, s57
	s_addc_u32 s9, s35, 0
	global_load_lds_dwordx4 v[6:7], off
	s_add_i32 m0, s29, 0x1c000
	v_lshl_add_u64 v[6:7], s[8:9], 0, v[134:135]
	global_load_lds_dwordx4 v[6:7], off
	v_lshl_add_u64 v[6:7], s[8:9], 0, v[138:139]
	s_add_i32 m0, s29, 0x1e000
	s_cmpk_lt_u32 s2, 0x100
	global_load_lds_dwordx4 v[6:7], off
	s_cselect_b64 s[8:9], -1, 0
	v_readlane_b32 s100, v253, 51
	s_nop 3
	s_cmp_lt_u32 s100, 4
	s_cbranch_scc1 .Lpro_nostag_4
	s_barrier
.Lpro_nostag_4:
	s_waitcnt vmcnt(8)
	s_barrier
	s_lshl_b32 s2, s6, 11
	s_lshl_b32 s6, s3, 4
	s_and_b32 s58, s6, 16
	s_cmp_lt_u32 s10, 2
	v_bitop3_b32 v1, v5, s7, v1 bitop3:0xde
	s_cselect_b64 s[6:7], -1, 0
	s_bfe_u32 s59, s3, 0x10001
	s_lshl_b32 s3, s10, 2
	s_add_i32 s3, s3, 0
	s_add_i32 s60, s3, s2
	v_readlane_b32 s2, v254, 28
	v_readlane_b32 s3, v254, 29
	s_mov_b32 s13, s3
	s_lshl_b32 s12, s70, 6
	v_readlane_b32 s64, v253, 15
	s_orn2_b32 s59, s59, 31
	s_mov_b32 s19, s3
	s_lshl_b64 s[2:3], s[12:13], 2
	v_readlane_b32 s78, v253, 29
	v_readlane_b32 s70, v253, 21
	v_readlane_b32 s71, v253, 22
	v_readlane_b32 s79, v253, 30
	s_add_u32 s10, s78, s2
	v_readlane_b32 s70, v254, 38
	s_addc_u32 s11, s79, s3
	s_mov_b32 s3, s13
	v_readlane_b32 s71, v254, 39
	s_lshl_b32 s12, s70, 7
	v_writelane_b32 v254, s2, 28
	s_waitcnt vmcnt(6)
	v_readlane_b32 s76, v253, 27
	v_readlane_b32 s77, v253, 28
	v_writelane_b32 v254, s3, 29
	s_lshl_b64 s[2:3], s[12:13], 2
	s_add_u32 s12, s76, s2
	s_addc_u32 s13, s77, s3
	s_add_i32 s60, s60, 0x20000
	s_mov_b32 s2, 0
	v_add_u32_e32 v5, 0, v14
	s_lshl_b64 s[14:15], s[18:19], 2
	s_barrier
	v_readlane_b32 s65, v253, 16
	v_readlane_b32 s66, v253, 17
	v_readlane_b32 s67, v253, 18
	v_readlane_b32 s68, v253, 19
	v_readlane_b32 s69, v253, 20
	v_readlane_b32 s72, v253, 23
	v_readlane_b32 s73, v253, 24
	v_readlane_b32 s74, v253, 25
	v_readlane_b32 s75, v253, 26
	s_branch .LBB0_447

.LBB0_474:
	v_and_b32_e32 v5, 48, v1
	v_lshlrev_b32_e32 v14, 6, v1
	s_movk_i32 s9, 0x3c0
	v_lshlrev_b32_e32 v1, 2, v1
	s_and_b32 s7, s8, 3
	s_lshl_b32 s8, s10, 13
	v_and_or_b32 v5, v14, s9, v5
	v_and_b32_e32 v1, 32, v1
	v_bitop3_b32 v14, v5, s8, v1 bitop3:0xde
	s_lshl_b32 s8, s7, 12
	v_bitop3_b32 v1, v5, s8, v1 bitop3:0xde
	s_mov_b64 s[8:9], 0x80
	s_add_i32 m0, s43, 0x18000
	v_lshl_add_u64 v[12:13], v[12:13], 0, s[8:9]
	global_load_lds_dwordx4 v[12:13], off
	v_lshl_add_u64 v[10:11], v[10:11], 0, s[8:9]
	s_add_i32 m0, s43, 0x1a000
	s_add_i32 s49, s43, 0x8000
	s_lshl_b32 s47, s10, 6
	s_lshl_b32 s48, s7, 5
	global_load_lds_dwordx4 v[10:11], off
	v_lshl_add_u64 v[6:7], v[6:7], 0, s[8:9]
	s_mov_b32 m0, s49
	s_add_i32 s50, s43, 0xa000
	global_load_lds_dwordx4 v[6:7], off
	v_lshl_add_u64 v[6:7], v[8:9], 0, s[8:9]
	s_add_u32 s8, s26, 0x20080
	s_mov_b32 m0, s50
	s_addc_u32 s9, s27, 0
	global_load_lds_dwordx4 v[6:7], off
	s_add_i32 m0, s43, 0x1c000
	v_lshl_add_u64 v[6:7], s[8:9], 0, v[134:135]
	global_load_lds_dwordx4 v[6:7], off
	v_lshl_add_u64 v[6:7], s[8:9], 0, v[138:139]
	s_add_i32 m0, s43, 0x1e000
	s_cmpk_lt_u32 s2, 0x100
	global_load_lds_dwordx4 v[6:7], off
	s_cselect_b64 s[8:9], -1, 0
	v_readlane_b32 s100, v253, 51
	s_nop 3
	s_cmp_lt_u32 s100, 4
	s_cbranch_scc1 .Lpro_nostag_5
	s_barrier
.Lpro_nostag_5:
	s_waitcnt vmcnt(8)
	s_barrier
	s_lshl_b32 s2, s10, 11
	s_lshl_b32 s7, s7, 2
	v_readlane_b32 s10, v254, 28
	s_add_i32 s7, s7, 0
	v_readlane_b32 s11, v254, 29
	s_lshl_b32 s10, s70, 7
	v_readlane_b32 s52, v253, 0
	s_waitcnt vmcnt(6)
	s_add_i32 s51, s7, s2
	s_mov_b32 s19, s11
	s_mov_b32 s7, s11
	s_lshl_b64 s[10:11], s[10:11], 2
	v_readlane_b32 s58, v253, 6
	v_writelane_b32 v254, s6, 28
	v_readlane_b32 s59, v253, 7
	s_add_u32 s10, s58, s10
	v_writelane_b32 v254, s7, 29
	s_addc_u32 s11, s59, s11
	s_add_i32 s51, s51, 0x20000
	s_mov_b32 s7, 0
	v_add_u32_e32 v5, 0, v14
	s_lshl_b64 s[12:13], s[18:19], 2
	s_barrier
	v_readlane_b32 s53, v253, 1
	v_readlane_b32 s54, v253, 2
	v_readlane_b32 s55, v253, 3
	v_readlane_b32 s56, v253, 4
	v_readlane_b32 s57, v253, 5
	s_branch .LBB0_477

.LBB0_528:
	v_and_b32_e32 v5, 48, v1
	v_lshlrev_b32_e32 v14, 6, v1
	s_movk_i32 s6, 0x3c0
	v_lshlrev_b32_e32 v1, 2, v1
	s_lshl_b32 s34, s0, 6
	s_lshl_b32 s0, s0, 13
	v_and_or_b32 v5, v14, s6, v5
	v_and_b32_e32 v1, 32, v1
	v_bitop3_b32 v14, v5, s0, v1 bitop3:0xde
	s_lshl_b32 s0, s1, 5
	s_and_b32 s35, s0, 0x60
	v_mov_b32_e32 v135, v4
	s_lshl_b32 s0, s35, 7
	v_lshl_add_u64 v[6:7], s[18:19], 0, v[134:135]
	v_mov_b32_e32 v139, v4
	v_bitop3_b32 v1, s0, v5, v1 bitop3:0xf6
	s_mov_b64 s[0:1], 0x80
	v_lshl_add_u64 v[8:9], s[18:19], 0, v[138:139]
	v_mov_b32_e32 v3, v4
	s_add_i32 m0, s15, 0x18000
	v_lshl_add_u64 v[6:7], v[6:7], 0, s[0:1]
	v_lshl_add_u64 v[10:11], s[20:21], 0, v[2:3]
	v_mov_b32_e32 v137, v4
	global_load_lds_dwordx4 v[6:7], off
	v_lshl_add_u64 v[6:7], v[8:9], 0, s[0:1]
	s_add_i32 m0, s15, 0x1a000
	s_add_i32 s38, s15, 0x8000
	v_lshl_add_u64 v[12:13], s[20:21], 0, v[136:137]
	global_load_lds_dwordx4 v[6:7], off
	v_lshl_add_u64 v[6:7], v[10:11], 0, s[0:1]
	s_mov_b32 m0, s38
	s_add_i32 s39, s15, 0xa000
	global_load_lds_dwordx4 v[6:7], off
	v_lshl_add_u64 v[6:7], v[12:13], 0, s[0:1]
	s_add_u32 s0, s18, 0x20080
	s_mov_b32 m0, s39
	s_addc_u32 s1, s19, 0
	global_load_lds_dwordx4 v[6:7], off
	s_add_i32 m0, s15, 0x1c000
	v_lshl_add_u64 v[6:7], s[0:1], 0, v[134:135]
	global_load_lds_dwordx4 v[6:7], off
	v_lshl_add_u64 v[6:7], s[0:1], 0, v[138:139]
	s_add_i32 m0, s15, 0x1e000
	s_mov_b32 s40, 0
	global_load_lds_dwordx4 v[6:7], off
	v_readlane_b32 s100, v253, 51
	s_nop 3
	s_cmp_lt_u32 s100, 4
	s_cbranch_scc1 .Lpro_nostag_6
	s_barrier
.Lpro_nostag_6:
	s_waitcnt vmcnt(8)
	s_barrier
	s_waitcnt vmcnt(6)
	v_add_u32_e32 v5, 0, v14
	s_barrier

.LBB0_915:
	v_and_b32_e32 v5, 48, v1
	v_lshlrev_b32_e32 v14, 6, v1
	s_movk_i32 s7, 0x3c0
	v_lshlrev_b32_e32 v1, 2, v1
	s_lshl_b32 s39, s0, 6
	s_lshl_b32 s0, s0, 13
	v_and_or_b32 v5, v14, s7, v5
	v_and_b32_e32 v1, 32, v1
	v_bitop3_b32 v14, v5, s0, v1 bitop3:0xde
	s_lshl_b32 s0, s1, 5
	s_and_b32 s40, s0, 0x60
	v_mov_b32_e32 v217, v4
	s_lshl_b32 s0, s40, 7
	v_lshl_add_u64 v[6:7], s[18:19], 0, v[216:217]
	v_mov_b32_e32 v221, v4
	v_bitop3_b32 v1, s0, v5, v1 bitop3:0xf6
	s_mov_b64 s[0:1], 0x80
	v_lshl_add_u64 v[8:9], s[18:19], 0, v[220:221]
	v_mov_b32_e32 v3, v4
	s_add_i32 m0, s35, 0x18000
	v_lshl_add_u64 v[6:7], v[6:7], 0, s[0:1]
	v_lshl_add_u64 v[10:11], s[20:21], 0, v[2:3]
	v_mov_b32_e32 v219, v4
	global_load_lds_dwordx4 v[6:7], off
	v_lshl_add_u64 v[6:7], v[8:9], 0, s[0:1]
	s_add_i32 m0, s35, 0x1a000
	s_add_i32 s41, s35, 0x8000
	v_lshl_add_u64 v[12:13], s[20:21], 0, v[218:219]
	global_load_lds_dwordx4 v[6:7], off
	v_lshl_add_u64 v[6:7], v[10:11], 0, s[0:1]
	s_mov_b32 m0, s41
	s_add_i32 s42, s35, 0xa000
	global_load_lds_dwordx4 v[6:7], off
	v_lshl_add_u64 v[6:7], v[12:13], 0, s[0:1]
	s_add_u32 s0, s18, 0x100080
	s_mov_b32 m0, s42
	s_addc_u32 s1, s19, 0
	global_load_lds_dwordx4 v[6:7], off
	s_add_i32 m0, s35, 0x1c000
	v_lshl_add_u64 v[6:7], s[0:1], 0, v[216:217]
	global_load_lds_dwordx4 v[6:7], off
	v_lshl_add_u64 v[6:7], s[0:1], 0, v[220:221]
	s_add_i32 m0, s35, 0x1e000
	s_mov_b32 s43, 0
	global_load_lds_dwordx4 v[6:7], off
	v_readlane_b32 s100, v253, 51
	s_nop 3
	s_cmp_lt_u32 s100, 4
	s_cbranch_scc1 .Lpro_nostag_7
	s_barrier
.Lpro_nostag_7:
	s_waitcnt vmcnt(8)
	s_barrier
	s_waitcnt vmcnt(6)
	v_add_u32_e32 v5, 0, v14
	s_barrier
	s_branch .LBB0_917

.LBB0_981:
	v_and_b32_e32 v5, 48, v1
	v_lshlrev_b32_e32 v20, 6, v1
	s_movk_i32 s11, 0x3c0
	v_lshlrev_b32_e32 v1, 2, v1
	v_mov_b32_e32 v9, v4
	s_lshl_b32 s40, s10, 6
	s_lshl_b32 s10, s10, 13
	v_and_or_b32 v5, v20, s11, v5
	v_and_b32_e32 v1, 32, v1
	v_lshl_add_u64 v[12:13], s[22:23], 0, v[8:9]
	v_mov_b32_e32 v3, v4
	v_bitop3_b32 v20, v5, s10, v1 bitop3:0xde
	s_mov_b64 s[10:11], 0x80
	v_lshl_add_u64 v[14:15], s[22:23], 0, v[2:3]
	v_mov_b32_e32 v11, v4
	s_lshl_b32 s9, s9, 5
	s_add_i32 m0, s1, 0x18000
	v_lshl_add_u64 v[12:13], v[12:13], 0, s[10:11]
	v_lshl_add_u64 v[16:17], s[20:21], 0, v[10:11]
	v_mov_b32_e32 v7, v4
	s_and_b32 s41, s9, 0x60
	global_load_lds_dwordx4 v[12:13], off
	v_lshl_add_u64 v[12:13], v[14:15], 0, s[10:11]
	s_add_i32 m0, s1, 0x1a000
	s_add_i32 s42, s1, 0x8000
	v_lshl_add_u64 v[18:19], s[20:21], 0, v[6:7]
	s_lshl_b32 s9, s41, 7
	global_load_lds_dwordx4 v[12:13], off
	v_lshl_add_u64 v[12:13], v[16:17], 0, s[10:11]
	s_mov_b32 m0, s42
	s_add_i32 s43, s1, 0xa000
	global_load_lds_dwordx4 v[12:13], off
	v_lshl_add_u64 v[12:13], v[18:19], 0, s[10:11]
	s_add_u32 s10, s22, 0x100080
	s_mov_b32 m0, s43
	s_addc_u32 s11, s23, 0
	global_load_lds_dwordx4 v[12:13], off
	s_add_i32 m0, s1, 0x1c000
	v_lshl_add_u64 v[12:13], s[10:11], 0, v[8:9]
	global_load_lds_dwordx4 v[12:13], off
	v_lshl_add_u64 v[12:13], s[10:11], 0, v[2:3]
	s_add_i32 m0, s1, 0x1e000
	s_add_i32 s8, s8, 1
	global_load_lds_dwordx4 v[12:13], off
	v_readlane_b32 s100, v253, 51
	s_nop 3
	s_cmp_lt_u32 s100, 4
	s_cbranch_scc1 .Lpro_nostag_8
	s_barrier
.Lpro_nostag_8:
	s_waitcnt vmcnt(8)
	s_barrier
	s_waitcnt vmcnt(6)
	v_bitop3_b32 v1, s9, v5, v1 bitop3:0xf6
	s_mul_i32 s44, s31, s8
	v_add_u32_e32 v5, 0, v20
	s_barrier
	s_branch .LBB0_983

	.amdhsa_kernel _Z10fwd_kernel6Params
		.amdhsa_group_segment_fixed_size 0
		.amdhsa_private_segment_fixed_size 0
		.amdhsa_kernarg_size 448
		.amdhsa_user_sgpr_count 2
		.amdhsa_user_sgpr_dispatch_ptr 0
		.amdhsa_user_sgpr_queue_ptr 0
		.amdhsa_user_sgpr_kernarg_segment_ptr 1
		.amdhsa_user_sgpr_dispatch_id 0
		.amdhsa_user_sgpr_kernarg_preload_length 0
		.amdhsa_user_sgpr_kernarg_preload_offset 0
		.amdhsa_user_sgpr_private_segment_size 0
		.amdhsa_uses_dynamic_stack 0
		.amdhsa_enable_private_segment 0
		.amdhsa_system_sgpr_workgroup_id_x 1
		.amdhsa_system_sgpr_workgroup_id_y 0
		.amdhsa_system_sgpr_workgroup_id_z 0
		.amdhsa_system_sgpr_workgroup_info 0
		.amdhsa_system_vgpr_workitem_id 0
		.amdhsa_next_free_vgpr 256
		.amdhsa_next_free_sgpr 102
		.amdhsa_accum_offset 256
		.amdhsa_reserve_vcc 1
		.amdhsa_float_round_mode_32 0
		.amdhsa_float_round_mode_16_64 0
		.amdhsa_float_denorm_mode_32 3
		.amdhsa_float_denorm_mode_16_64 3
		.amdhsa_dx10_clamp 1
		.amdhsa_ieee_mode 1
		.amdhsa_fp16_overflow 0
		.amdhsa_tg_split 0
		.amdhsa_exception_fp_ieee_invalid_op 0
		.amdhsa_exception_fp_denorm_src 0
		.amdhsa_exception_fp_ieee_div_zero 0
		.amdhsa_exception_fp_ieee_overflow 0
		.amdhsa_exception_fp_ieee_underflow 0
		.amdhsa_exception_fp_ieee_inexact 0
		.amdhsa_exception_int_div_zero 0
	.end_amdhsa_kernel

amdhsa.kernels:
  - .agpr_count:     0
    .args:
      - .offset:         0
        .size:           192
        .value_kind:     by_value
      - .offset:         192
        .size:           4
        .value_kind:     hidden_block_count_x
      - .offset:         196
        .size:           4
        .value_kind:     hidden_block_count_y
      - .offset:         200
        .size:           4
        .value_kind:     hidden_block_count_z
      - .offset:         204
        .size:           2
        .value_kind:     hidden_group_size_x
      - .offset:         206
        .size:           2
        .value_kind:     hidden_group_size_y
      - .offset:         208
        .size:           2
        .value_kind:     hidden_group_size_z
      - .offset:         210
        .size:           2
        .value_kind:     hidden_remainder_x
      - .offset:         212
        .size:           2
        .value_kind:     hidden_remainder_y
      - .offset:         214
        .size:           2
        .value_kind:     hidden_remainder_z
      - .offset:         232
        .size:           8
        .value_kind:     hidden_global_offset_x
      - .offset:         240
        .size:           8
        .value_kind:     hidden_global_offset_y
      - .offset:         248
        .size:           8
        .value_kind:     hidden_global_offset_z
      - .offset:         256
        .size:           2
        .value_kind:     hidden_grid_dims
      - .offset:         312
        .size:           4
        .value_kind:     hidden_dynamic_lds_size
    .group_segment_fixed_size: 0
    .kernarg_segment_align: 8
    .kernarg_segment_size: 448
    .language:       OpenCL C
    .language_version:
      - 2
      - 0
    .max_flat_workgroup_size: 512
    .name:           _Z10fwd_kernel6Params
    .private_segment_fixed_size: 0
    .sgpr_count:     108
    .sgpr_spill_count: 179
    .symbol:         _Z10fwd_kernel6Params.kd
    .uniform_work_group_size: 1
    .uses_dynamic_stack: false
    .vgpr_count:     256
    .vgpr_spill_count: 0
    .wavefront_size: 64
